# P2a sgu prompt items: MFMA loop reads all 8 A fragments up front with counted lgkmcnt waits (was read-wait-MFMA x8), W->Wm conversion loads hoisted (one wait instead of four rounds)
# speedup vs baseline: 1.0046x; 1.0046x over previous
; __device__ __forceinline__ float bf2f(unsigned b) { return __uint_as_float(b << 16); }
; __device__ __forceinline__ unsigned pk2(float lo, float hi) { unsigned r; asm("v_cvt_pk_bf16_f32 %0, %1, %2" : "=v"(r) : "v"(lo), "v"(hi)); return r; }
; __device__ __forceinline__ f32x4 mma16(bf16x8 a, bf16x8 b, f32x4 c) { return __builtin_amdgcn_mfma_f32_16x16x32_bf16(a, b, c, 0, 0, 0); }
; __device__ __forceinline__ void sgu_prompt_item(int item, const u16* PROJ, u16* MIXIN, const float* gln, const float* bln, const float* wsp, const float* bsp, LAS unsigned char* lds, int& hh_cached) {
;     ...
;     for (int ks = 0; ks <= (w >> 1); ++ks) { const bf16x8 b = frag(Wm, 16 * w, LD2, ks * 32, lane);
; #pragma unroll
;         for (int dct = 0; dct < 8; ++dct) acc[dct] = mma16(frag(VnT, dct * 16, LD2, ks * 32, lane), b, acc[dct]); }
;     { const int t = 16 * w + (lane & 15); const size_t row = row0 + t;
; #pragma unroll
;       for (int dct = 0; dct < 8; ++dct) { const int dc = 16 * dct + (lane >> 4) * 4;
;           u32x2 ov; ov.x = pk2(bf2f(uw[dct].x & 0xffffu) * (acc[dct].x + bs), bf2f(uw[dct].x >> 16) * (acc[dct].y + bs));
;           ov.y = pk2(bf2f(uw[dct].y & 0xffffu) * (acc[dct].z + bs), bf2f(uw[dct].y >> 16) * (acc[dct].w + bs));
;           *(u32x2*)(MIXIN + row * D + 512 + hh * 128 + dc) = ov; } }
.LBB0_241:
	ds_read_b128 v[156:159], v52
	ds_read_b128 v[204:207], v81
	ds_read_b128 v[208:211], v81 offset:4352
	ds_read_b128 v[212:215], v81 offset:8704
	ds_read_b128 v[216:219], v81 offset:13056
	ds_read_b128 v[220:223], v81 offset:17408
	ds_read_b128 v[224:227], v81 offset:21760
	ds_read_b128 v[228:231], v81 offset:26112
	ds_read_b128 v[232:235], v81 offset:30464
	s_add_i32 s6, s6, -1
	v_add_u32_e32 v52, 64, v52
	v_add_u32_e32 v81, 64, v81
	s_cmp_lg_u32 s6, 0
	s_waitcnt lgkmcnt(7)
	v_mfma_f32_16x16x32_bf16 v[28:31], v[204:207], v[156:159], v[28:31]
	s_waitcnt lgkmcnt(6)
	v_mfma_f32_16x16x32_bf16 v[24:27], v[208:211], v[156:159], v[24:27]
	s_waitcnt lgkmcnt(5)
	v_mfma_f32_16x16x32_bf16 v[20:23], v[212:215], v[156:159], v[20:23]
	s_waitcnt lgkmcnt(4)
	v_mfma_f32_16x16x32_bf16 v[16:19], v[216:219], v[156:159], v[16:19]
	s_waitcnt lgkmcnt(3)
	v_mfma_f32_16x16x32_bf16 v[12:15], v[220:223], v[156:159], v[12:15]
	s_waitcnt lgkmcnt(2)
	v_mfma_f32_16x16x32_bf16 v[8:11], v[224:227], v[156:159], v[8:11]
	s_waitcnt lgkmcnt(1)
	v_mfma_f32_16x16x32_bf16 v[4:7], v[228:231], v[156:159], v[4:7]
	s_waitcnt lgkmcnt(0)
	v_mfma_f32_16x16x32_bf16 v[0:3], v[232:235], v[156:159], v[0:3]
	s_cbranch_scc1 .LBB0_241
	v_or_b32_e32 v52, s54, v64
	v_lshl_add_u64 v[156:157], s[78:79], 0, v[52:53]
	v_lshlrev_b32_e32 v52, 16, v104
	v_add_f32_e32 v28, v79, v28
	v_mul_f32_e32 v28, v28, v52
	v_and_b32_e32 v52, 0xffff0000, v104
	v_add_f32_e32 v29, v79, v29
	v_mul_f32_e32 v29, v29, v52
	v_lshlrev_b64 v[156:157], 11, v[156:157]
	v_cvt_pk_bf16_f32 v28, v28, v29
	v_lshlrev_b32_e32 v29, 16, v105
	v_add_f32_e32 v30, v79, v30
	v_lshl_add_u64 v[156:157], s[52:53], 0, v[156:157]
	s_lshl_b32 s6, s35, 1
	v_mul_f32_e32 v29, v30, v29
	v_and_b32_e32 v30, 0xffff0000, v105
	v_add_f32_e32 v31, v79, v31
	v_lshl_add_u64 v[156:157], v[156:157], 0, s[6:7]
	v_mul_f32_e32 v30, v31, v30
	v_mov_b32_e32 v103, v53
	v_cvt_pk_bf16_f32 v29, v29, v30
	v_lshl_add_u64 v[30:31], v[156:157], 0, v[102:103]
	global_store_dwordx2 v[30:31], v[28:29], off offset:1024
	v_lshlrev_b32_e32 v28, 16, v100
	v_add_f32_e32 v24, v79, v24
	v_mul_f32_e32 v24, v24, v28
	v_and_b32_e32 v28, 0xffff0000, v100
	v_add_f32_e32 v25, v79, v25
	v_mul_f32_e32 v25, v25, v28
	v_cvt_pk_bf16_f32 v24, v24, v25
	v_lshlrev_b32_e32 v25, 16, v101
	v_add_f32_e32 v26, v79, v26
	v_mul_f32_e32 v25, v26, v25
	v_and_b32_e32 v26, 0xffff0000, v101
	v_add_f32_e32 v27, v79, v27
	v_mul_f32_e32 v26, v27, v26
	v_cvt_pk_bf16_f32 v25, v25, v26
	global_store_dwordx2 v[30:31], v[24:25], off offset:1056
	v_lshlrev_b32_e32 v24, 16, v98
	v_add_f32_e32 v20, v79, v20
	v_mul_f32_e32 v20, v20, v24
	v_and_b32_e32 v24, 0xffff0000, v98
	v_add_f32_e32 v21, v79, v21
	v_mul_f32_e32 v21, v21, v24
	v_cvt_pk_bf16_f32 v20, v20, v21
	v_lshlrev_b32_e32 v21, 16, v99
	v_add_f32_e32 v22, v79, v22
	v_mul_f32_e32 v21, v22, v21
	v_and_b32_e32 v22, 0xffff0000, v99
	v_add_f32_e32 v23, v79, v23
	v_mul_f32_e32 v22, v23, v22
	v_cvt_pk_bf16_f32 v21, v21, v22
	global_store_dwordx2 v[30:31], v[20:21], off offset:1088
	v_lshlrev_b32_e32 v20, 16, v96
	v_add_f32_e32 v16, v79, v16
	v_mul_f32_e32 v16, v16, v20
	v_and_b32_e32 v20, 0xffff0000, v96
	v_add_f32_e32 v17, v79, v17
	v_mul_f32_e32 v17, v17, v20
	v_cvt_pk_bf16_f32 v16, v16, v17
	v_lshlrev_b32_e32 v17, 16, v97
	v_add_f32_e32 v18, v79, v18
	v_mul_f32_e32 v17, v18, v17
	v_and_b32_e32 v18, 0xffff0000, v97
	v_add_f32_e32 v19, v79, v19
	v_mul_f32_e32 v18, v19, v18
	v_cvt_pk_bf16_f32 v17, v17, v18
	global_store_dwordx2 v[30:31], v[16:17], off offset:1120
	v_lshlrev_b32_e32 v16, 16, v94
	v_add_f32_e32 v12, v79, v12
	v_mul_f32_e32 v12, v12, v16
	v_and_b32_e32 v16, 0xffff0000, v94
	v_add_f32_e32 v13, v79, v13
	v_mul_f32_e32 v13, v13, v16
	v_cvt_pk_bf16_f32 v12, v12, v13
	v_lshlrev_b32_e32 v13, 16, v95
	v_add_f32_e32 v14, v79, v14
	v_mul_f32_e32 v13, v14, v13
	v_and_b32_e32 v14, 0xffff0000, v95
	v_add_f32_e32 v15, v79, v15
	v_mul_f32_e32 v14, v15, v14
	v_cvt_pk_bf16_f32 v13, v13, v14
	global_store_dwordx2 v[30:31], v[12:13], off offset:1152
	v_lshlrev_b32_e32 v12, 16, v92
	v_add_f32_e32 v8, v79, v8
	v_mul_f32_e32 v8, v8, v12
	v_and_b32_e32 v12, 0xffff0000, v92
	v_add_f32_e32 v9, v79, v9
	v_mul_f32_e32 v9, v9, v12
	v_cvt_pk_bf16_f32 v8, v8, v9
	v_lshlrev_b32_e32 v9, 16, v93
	v_add_f32_e32 v10, v79, v10
	v_mul_f32_e32 v9, v10, v9
	v_and_b32_e32 v10, 0xffff0000, v93
	v_add_f32_e32 v11, v79, v11
	v_mul_f32_e32 v10, v11, v10
	v_cvt_pk_bf16_f32 v9, v9, v10
	global_store_dwordx2 v[30:31], v[8:9], off offset:1184
	v_lshlrev_b32_e32 v8, 16, v90
	v_add_f32_e32 v4, v79, v4
	v_mul_f32_e32 v4, v4, v8
	v_and_b32_e32 v8, 0xffff0000, v90
	v_add_f32_e32 v5, v79, v5
	v_mul_f32_e32 v5, v5, v8
	v_cvt_pk_bf16_f32 v4, v4, v5
	v_lshlrev_b32_e32 v5, 16, v91
	v_add_f32_e32 v6, v79, v6
	v_mul_f32_e32 v5, v6, v5
	v_and_b32_e32 v6, 0xffff0000, v91
	v_add_f32_e32 v7, v79, v7
	v_mul_f32_e32 v6, v7, v6
	v_cvt_pk_bf16_f32 v5, v5, v6
	global_store_dwordx2 v[30:31], v[4:5], off offset:1216
	v_lshlrev_b32_e32 v4, 16, v88
	v_add_f32_e32 v0, v79, v0
	v_mul_f32_e32 v0, v0, v4
	v_and_b32_e32 v4, 0xffff0000, v88
	v_add_f32_e32 v1, v79, v1
	v_mul_f32_e32 v1, v1, v4
	v_cvt_pk_bf16_f32 v0, v0, v1
	v_lshlrev_b32_e32 v1, 16, v89
	v_add_f32_e32 v2, v79, v2
	v_mul_f32_e32 v1, v2, v1
	v_and_b32_e32 v2, 0xffff0000, v89
	v_add_f32_e32 v3, v79, v3
	v_mul_f32_e32 v2, v3, v2
	v_cvt_pk_bf16_f32 v1, v1, v2
	global_store_dwordx2 v[30:31], v[0:1], off offset:1248
	s_waitcnt lgkmcnt(0)
	s_barrier
	s_add_i32 s50, s50, s14
	s_cmpk_gt_i32 s50, 0x7ff
	s_cbranch_scc0 .LBB0_224
	s_branch .LBB0_248
